# GEMM K-loop: one s_nop before/after the third MFMA segment so every 32-MFMA run starts 8-byte aligned
# speedup vs baseline: 1.0056x; 1.0010x over previous
; #define PG8_STAGE(bufoff, gbase, voff) do { _Pragma("unroll") for (int _i = 0; _i < 2; ++_i) \
;         __builtin_amdgcn_global_load_lds((const unsigned*)((const char*)(gbase) + (voff)[_i]), (PG8_LAS unsigned*)(lds + (bufoff) + ldsw + _i * 8192), 16, 0, 0); } while (0)
; #define PG8_LDA(dst, b, h) do { _Pragma("unroll") for (int m = 0; m < 4; ++m) _Pragma("unroll") for (int k = 0; k < 2; ++k) dst[m][k] = *(const PG8_LAS bf16x8*)(lds + PG8_SA(b, h) + aoff + m * 2048 + k * 1024); } while (0)
; #define PG8_LDB(dst, b, h) do { _Pragma("unroll") for (int n = 0; n < 2; ++n) _Pragma("unroll") for (int k = 0; k < 2; ++k) dst[n][k] = *(const PG8_LAS bf16x8*)(lds + PG8_SB(b, h) + boff + n * 2048 + k * 1024); } while (0)
; #define PG8_MMA(ai, bj, At, Bt) do { __builtin_amdgcn_s_setprio(1); _Pragma("unroll") for (int m = 0; m < 4; ++m) _Pragma("unroll") for (int n = 0; n < 2; ++n) _Pragma("unroll") for (int k = 0; k < 2; ++k) \
;         acc[ai][bj][m][n] = __builtin_amdgcn_mfma_f32_16x16x32_bf16(Bt[n][k], At[m][k], acc[ai][bj][m][n], 0, 0, 0); __builtin_amdgcn_s_setprio(0); } while (0)
; #define PG8_WAIT_V(n) asm volatile("s_waitcnt vmcnt(" #n ")" ::: "memory")
; #define PG8_WAIT_L(n) asm volatile("s_waitcnt lgkmcnt(" #n ")" ::: "memory")
; #define PG8_BAR __builtin_amdgcn_s_barrier()
; #define PG8_SCHED __builtin_amdgcn_sched_barrier(0)
; template <class Epi, class Sched, bool ALIGN_EPI = false, bool SP2 = false>
; __device__ __forceinline__ void gemm_phase(PG8_LAS unsigned char* lds, const Gemm g, const Sched& S, const Epi& E) {
;     ...
;             const bool last = (t == nt - 2);
;             const char* a1 = cA + (size_t)(t + 1) * kstepB;
;             const char* a2 = last ? nA : cA + (size_t)(t + 2) * kstepB; const char* b2 = last ? nB : cB + (size_t)(t + 2) * kstepB;
;             const char* a3 = a2 + kstepB; const char* b3 = b2 + kstepB;
;             if (last && has_next) S.a_ready(nxt);
;             if constexpr (SP2) {
;             PG8_LDB(B0, 0, 0); PG8_LDB(B1, 0, 1); PG8_SCHED; PG8_LDA(At, 0, 0); PG8_STAGE(PG8_SA(1, 1), a1 + hstepB, voffA);
;             PG8_WAIT_V(8); PG8_WAIT_L(0); PG8_BAR; PG8_MMA(0, 0, At, B0); PG8_MMA(0, 1, At, B1); PG8_BAR; PG8_SCHED;
;             PG8_LDA(At, 0, 1); PG8_STAGE(PG8_SB(0, 0), b2, voffB); PG8_STAGE(PG8_SB(0, 1), b2 + hstepB, voffB); PG8_STAGE(PG8_SA(0, 0), a2, voffA);
.LBB0_193:
	s_add_i32 s84, s38, 2
	s_add_u32 s39, s36, 0x4000
	s_addc_u32 s40, s37, 0
	s_cmp_eq_u32 s31, s38
	s_cselect_b32 s42, s8, s39
	s_cselect_b32 s43, s9, s40
	s_cselect_b32 s40, s62, s78
	s_cselect_b32 s41, s63, s82
	s_add_u32 s38, s42, 0x8000
	s_addc_u32 s39, s43, 0
	s_add_i32 s90, 0, 0x10000
	s_add_i32 s64, 0, 0x14000
	v_add_u32_e32 v140, s90, v174
	v_add_u32_e32 v161, s64, v174
	ds_read_b128 v[128:131], v140
	ds_read_b128 v[132:135], v140 offset:1024
	ds_read_b128 v[136:139], v140 offset:2048
	ds_read_b128 v[140:143], v140 offset:3072
	ds_read_b128 v[144:147], v161
	ds_read_b128 v[148:151], v161 offset:1024
	ds_read_b128 v[178:181], v161 offset:2048
	ds_read_b128 v[182:185], v161 offset:3072
	v_lshl_add_u64 v[172:173], s[36:37], 0, v[168:169]
	s_add_i32 m0, s21, 0xc000
	ds_read_b128 v[186:189], v177
	ds_read_b128 v[190:193], v177 offset:1024
	ds_read_b128 v[194:197], v177 offset:2048
	ds_read_b128 v[198:201], v177 offset:3072
	ds_read_b128 v[202:205], v177 offset:4096
	ds_read_b128 v[206:209], v177 offset:5120
	ds_read_b128 v[210:213], v177 offset:6144
	ds_read_b128 v[214:217], v177 offset:7168
	global_load_lds_dwordx4 v[172:173], off
	v_lshl_add_u64 v[172:173], s[36:37], 0, v[170:171]
	s_add_i32 m0, s21, 0xe000
	s_nop 0
	global_load_lds_dwordx4 v[172:173], off
	s_waitcnt vmcnt(8)
	s_waitcnt lgkmcnt(0)
	s_barrier
	s_setprio 1
	s_waitcnt lgkmcnt(0)
	v_mfma_f32_16x16x32_bf16 v[124:127], v[128:131], v[186:189], v[124:127]
	v_mfma_f32_16x16x32_bf16 v[124:127], v[132:135], v[190:193], v[124:127]
	v_mfma_f32_16x16x32_bf16 v[120:123], v[136:139], v[186:189], v[120:123]
	v_mfma_f32_16x16x32_bf16 v[120:123], v[140:143], v[190:193], v[120:123]
	v_mfma_f32_16x16x32_bf16 v[108:111], v[128:131], v[194:197], v[108:111]
	v_mfma_f32_16x16x32_bf16 v[108:111], v[132:135], v[198:201], v[108:111]
	v_mfma_f32_16x16x32_bf16 v[104:107], v[136:139], v[194:197], v[104:107]
	v_mfma_f32_16x16x32_bf16 v[104:107], v[140:143], v[198:201], v[104:107]
	v_mfma_f32_16x16x32_bf16 v[92:95], v[128:131], v[202:205], v[92:95]
	v_mfma_f32_16x16x32_bf16 v[92:95], v[132:135], v[206:209], v[92:95]
	v_mfma_f32_16x16x32_bf16 v[88:91], v[136:139], v[202:205], v[88:91]
	v_mfma_f32_16x16x32_bf16 v[88:91], v[140:143], v[206:209], v[88:91]
	v_mfma_f32_16x16x32_bf16 v[76:79], v[128:131], v[210:213], v[76:79]
	v_mfma_f32_16x16x32_bf16 v[76:79], v[132:135], v[214:217], v[76:79]
	v_mfma_f32_16x16x32_bf16 v[72:75], v[136:139], v[210:213], v[72:75]
	v_mfma_f32_16x16x32_bf16 v[72:75], v[140:143], v[214:217], v[72:75]
	s_setprio 0
	s_setprio 1
	v_mfma_f32_16x16x32_bf16 v[116:119], v[144:147], v[186:189], v[116:119]
	v_mfma_f32_16x16x32_bf16 v[116:119], v[148:151], v[190:193], v[116:119]
	v_mfma_f32_16x16x32_bf16 v[112:115], v[178:181], v[186:189], v[112:115]
	v_mfma_f32_16x16x32_bf16 v[112:115], v[182:185], v[190:193], v[112:115]
	v_mfma_f32_16x16x32_bf16 v[100:103], v[144:147], v[194:197], v[100:103]
	v_mfma_f32_16x16x32_bf16 v[100:103], v[148:151], v[198:201], v[100:103]
	v_mfma_f32_16x16x32_bf16 v[96:99], v[178:181], v[194:197], v[96:99]
	v_mfma_f32_16x16x32_bf16 v[96:99], v[182:185], v[198:201], v[96:99]
	v_mfma_f32_16x16x32_bf16 v[84:87], v[144:147], v[202:205], v[84:87]
	v_mfma_f32_16x16x32_bf16 v[84:87], v[148:151], v[206:209], v[84:87]
	v_mfma_f32_16x16x32_bf16 v[80:83], v[178:181], v[202:205], v[80:83]
	v_mfma_f32_16x16x32_bf16 v[80:83], v[182:185], v[206:209], v[80:83]
	v_mfma_f32_16x16x32_bf16 v[68:71], v[144:147], v[210:213], v[68:71]
	v_mfma_f32_16x16x32_bf16 v[68:71], v[148:151], v[214:217], v[68:71]
	v_mfma_f32_16x16x32_bf16 v[64:67], v[178:181], v[210:213], v[64:67]
	v_mfma_f32_16x16x32_bf16 v[64:67], v[182:185], v[214:217], v[64:67]
	s_setprio 0
	s_barrier
	s_add_i32 s65, s90, s20
	v_lshl_add_u64 v[172:173], s[40:41], 0, v[156:157]
	s_mov_b32 m0, s65
	ds_read_b128 v[186:189], v177 offset:16384
	ds_read_b128 v[190:193], v177 offset:17408
	ds_read_b128 v[194:197], v177 offset:18432
	ds_read_b128 v[198:201], v177 offset:19456
	ds_read_b128 v[202:205], v177 offset:20480
	ds_read_b128 v[206:209], v177 offset:21504
	ds_read_b128 v[210:213], v177 offset:22528
	ds_read_b128 v[214:217], v177 offset:23552
	global_load_lds_dwordx4 v[172:173], off
	s_add_i32 m0, s65, 0x2000
	s_add_u32 vcc_lo, s40, 0x4000
	v_lshl_add_u64 v[172:173], s[40:41], 0, v[152:153]
	s_addc_u32 vcc_hi, s41, 0
	s_add_i32 s64, s64, s20
	global_load_lds_dwordx4 v[172:173], off
	v_lshl_add_u64 v[172:173], vcc, 0, v[156:157]
	s_mov_b32 m0, s64
	s_nop 0
	global_load_lds_dwordx4 v[172:173], off
	v_lshl_add_u64 v[172:173], vcc, 0, v[152:153]
	s_add_i32 m0, s64, 0x2000
	s_nop 0
	global_load_lds_dwordx4 v[172:173], off
	v_lshl_add_u64 v[172:173], s[42:43], 0, v[158:159]
	s_mov_b32 m0, s21
	s_nop 0
	global_load_lds_dwordx4 v[172:173], off
	v_lshl_add_u64 v[172:173], s[42:43], 0, v[154:155]
	s_mov_b32 m0, s22
	s_nop 0
	global_load_lds_dwordx4 v[172:173], off
	s_waitcnt vmcnt(8)
	s_waitcnt lgkmcnt(0)
	s_barrier
; #define PG8_STAGE(bufoff, gbase, voff) do { _Pragma("unroll") for (int _i = 0; _i < 2; ++_i) \
;         __builtin_amdgcn_global_load_lds((const unsigned*)((const char*)(gbase) + (voff)[_i]), (PG8_LAS unsigned*)(lds + (bufoff) + ldsw + _i * 8192), 16, 0, 0); } while (0)
; #define PG8_LDA(dst, b, h) do { _Pragma("unroll") for (int m = 0; m < 4; ++m) _Pragma("unroll") for (int k = 0; k < 2; ++k) dst[m][k] = *(const PG8_LAS bf16x8*)(lds + PG8_SA(b, h) + aoff + m * 2048 + k * 1024); } while (0)
; #define PG8_LDB(dst, b, h) do { _Pragma("unroll") for (int n = 0; n < 2; ++n) _Pragma("unroll") for (int k = 0; k < 2; ++k) dst[n][k] = *(const PG8_LAS bf16x8*)(lds + PG8_SB(b, h) + boff + n * 2048 + k * 1024); } while (0)
; #define PG8_MMA(ai, bj, At, Bt) do { __builtin_amdgcn_s_setprio(1); _Pragma("unroll") for (int m = 0; m < 4; ++m) _Pragma("unroll") for (int n = 0; n < 2; ++n) _Pragma("unroll") for (int k = 0; k < 2; ++k) \
;         acc[ai][bj][m][n] = __builtin_amdgcn_mfma_f32_16x16x32_bf16(Bt[n][k], At[m][k], acc[ai][bj][m][n], 0, 0, 0); __builtin_amdgcn_s_setprio(0); } while (0)
; #define PG8_WAIT_V(n) asm volatile("s_waitcnt vmcnt(" #n ")" ::: "memory")
; #define PG8_WAIT_L(n) asm volatile("s_waitcnt lgkmcnt(" #n ")" ::: "memory")
; #define PG8_BAR __builtin_amdgcn_s_barrier()
; #define PG8_SCHED __builtin_amdgcn_sched_barrier(0)
; template <class Epi, class Sched, bool ALIGN_EPI = false, bool SP2 = false>
; __device__ __forceinline__ void gemm_phase(PG8_LAS unsigned char* lds, const Gemm g, const Sched& S, const Epi& E) {
;     ...
;             PG8_WAIT_V(8); PG8_WAIT_L(0); PG8_BAR; PG8_MMA(1, 0, At, B0); PG8_MMA(1, 1, At, B1); PG8_BAR; PG8_SCHED;
;             PG8_LDB(B0, 1, 0); PG8_LDB(B1, 1, 1); PG8_SCHED; PG8_LDA(At, 1, 0); PG8_STAGE(PG8_SA(0, 1), a2 + hstepB, voffA);
;             PG8_WAIT_V(8); PG8_WAIT_L(0); PG8_BAR; PG8_MMA(0, 0, At, B0); PG8_MMA(0, 1, At, B1); PG8_BAR; PG8_SCHED;
	s_setprio 1
	s_waitcnt lgkmcnt(0)
	v_mfma_f32_16x16x32_bf16 v[60:63], v[128:131], v[186:189], v[60:63]
	v_mfma_f32_16x16x32_bf16 v[60:63], v[132:135], v[190:193], v[60:63]
	v_mfma_f32_16x16x32_bf16 v[56:59], v[136:139], v[186:189], v[56:59]
	v_mfma_f32_16x16x32_bf16 v[56:59], v[140:143], v[190:193], v[56:59]
	v_mfma_f32_16x16x32_bf16 v[44:47], v[128:131], v[194:197], v[44:47]
	v_mfma_f32_16x16x32_bf16 v[44:47], v[132:135], v[198:201], v[44:47]
	v_mfma_f32_16x16x32_bf16 v[40:43], v[136:139], v[194:197], v[40:43]
	v_mfma_f32_16x16x32_bf16 v[40:43], v[140:143], v[198:201], v[40:43]
	v_mfma_f32_16x16x32_bf16 v[28:31], v[128:131], v[202:205], v[28:31]
	v_mfma_f32_16x16x32_bf16 v[28:31], v[132:135], v[206:209], v[28:31]
	v_mfma_f32_16x16x32_bf16 v[24:27], v[136:139], v[202:205], v[24:27]
	v_mfma_f32_16x16x32_bf16 v[24:27], v[140:143], v[206:209], v[24:27]
	v_mfma_f32_16x16x32_bf16 v[12:15], v[128:131], v[210:213], v[12:15]
	v_mfma_f32_16x16x32_bf16 v[12:15], v[132:135], v[214:217], v[12:15]
	v_mfma_f32_16x16x32_bf16 v[8:11], v[136:139], v[210:213], v[8:11]
	v_mfma_f32_16x16x32_bf16 v[8:11], v[140:143], v[214:217], v[8:11]
	s_setprio 0
	s_setprio 1
	v_mfma_f32_16x16x32_bf16 v[52:55], v[144:147], v[186:189], v[52:55]
	v_mfma_f32_16x16x32_bf16 v[52:55], v[148:151], v[190:193], v[52:55]
	v_mfma_f32_16x16x32_bf16 v[48:51], v[178:181], v[186:189], v[48:51]
	v_mfma_f32_16x16x32_bf16 v[48:51], v[182:185], v[190:193], v[48:51]
	v_mfma_f32_16x16x32_bf16 v[36:39], v[144:147], v[194:197], v[36:39]
	v_mfma_f32_16x16x32_bf16 v[36:39], v[148:151], v[198:201], v[36:39]
	v_mfma_f32_16x16x32_bf16 v[32:35], v[178:181], v[194:197], v[32:35]
	v_mfma_f32_16x16x32_bf16 v[32:35], v[182:185], v[198:201], v[32:35]
	v_mfma_f32_16x16x32_bf16 v[20:23], v[144:147], v[202:205], v[20:23]
	v_mfma_f32_16x16x32_bf16 v[20:23], v[148:151], v[206:209], v[20:23]
	v_mfma_f32_16x16x32_bf16 v[16:19], v[178:181], v[202:205], v[16:19]
	v_mfma_f32_16x16x32_bf16 v[16:19], v[182:185], v[206:209], v[16:19]
	v_mfma_f32_16x16x32_bf16 v[4:7], v[144:147], v[210:213], v[4:7]
	v_mfma_f32_16x16x32_bf16 v[4:7], v[148:151], v[214:217], v[4:7]
	v_mfma_f32_16x16x32_bf16 v[0:3], v[178:181], v[210:213], v[0:3]
	v_mfma_f32_16x16x32_bf16 v[0:3], v[182:185], v[214:217], v[0:3]
	s_setprio 0
	s_barrier
	s_add_i32 s64, 0, 0x18000
	s_add_i32 s65, 0, 0x1c000
	v_add_u32_e32 v140, s64, v174
	v_add_u32_e32 v161, s65, v174
	ds_read_b128 v[128:131], v140
	ds_read_b128 v[132:135], v140 offset:1024
	ds_read_b128 v[136:139], v140 offset:2048
	ds_read_b128 v[140:143], v140 offset:3072
	ds_read_b128 v[144:147], v161
	ds_read_b128 v[148:151], v161 offset:1024
	ds_read_b128 v[178:181], v161 offset:2048
	ds_read_b128 v[182:185], v161 offset:3072
	s_add_u32 s42, s42, 0x4000
	s_addc_u32 s43, s43, 0
	s_mov_b32 m0, s23
	v_lshl_add_u64 v[172:173], s[42:43], 0, v[158:159]
	ds_read_b128 v[186:189], v177 offset:32768
	ds_read_b128 v[190:193], v177 offset:33792
	ds_read_b128 v[194:197], v177 offset:34816
	ds_read_b128 v[198:201], v177 offset:35840
	ds_read_b128 v[202:205], v177 offset:36864
	ds_read_b128 v[206:209], v177 offset:37888
	ds_read_b128 v[210:213], v177 offset:38912
	ds_read_b128 v[214:217], v177 offset:39936
	global_load_lds_dwordx4 v[172:173], off
	v_lshl_add_u64 v[172:173], s[42:43], 0, v[154:155]
	s_mov_b32 m0, s24
	s_nop 0
	global_load_lds_dwordx4 v[172:173], off
	s_nop 0
	s_waitcnt vmcnt(8)
	s_waitcnt lgkmcnt(0)
	s_barrier
	s_setprio 1
	s_waitcnt lgkmcnt(0)
	v_mfma_f32_16x16x32_bf16 v[124:127], v[128:131], v[186:189], v[124:127]
	v_mfma_f32_16x16x32_bf16 v[124:127], v[132:135], v[190:193], v[124:127]
	v_mfma_f32_16x16x32_bf16 v[120:123], v[136:139], v[186:189], v[120:123]
	v_mfma_f32_16x16x32_bf16 v[120:123], v[140:143], v[190:193], v[120:123]
	v_mfma_f32_16x16x32_bf16 v[108:111], v[128:131], v[194:197], v[108:111]
	v_mfma_f32_16x16x32_bf16 v[108:111], v[132:135], v[198:201], v[108:111]
	v_mfma_f32_16x16x32_bf16 v[104:107], v[136:139], v[194:197], v[104:107]
	v_mfma_f32_16x16x32_bf16 v[104:107], v[140:143], v[198:201], v[104:107]
	v_mfma_f32_16x16x32_bf16 v[92:95], v[128:131], v[202:205], v[92:95]
	v_mfma_f32_16x16x32_bf16 v[92:95], v[132:135], v[206:209], v[92:95]
	v_mfma_f32_16x16x32_bf16 v[88:91], v[136:139], v[202:205], v[88:91]
	v_mfma_f32_16x16x32_bf16 v[88:91], v[140:143], v[206:209], v[88:91]
	v_mfma_f32_16x16x32_bf16 v[76:79], v[128:131], v[210:213], v[76:79]
	v_mfma_f32_16x16x32_bf16 v[76:79], v[132:135], v[214:217], v[76:79]
	v_mfma_f32_16x16x32_bf16 v[72:75], v[136:139], v[210:213], v[72:75]
	v_mfma_f32_16x16x32_bf16 v[72:75], v[140:143], v[214:217], v[72:75]
	s_setprio 0
	s_setprio 1
	v_mfma_f32_16x16x32_bf16 v[116:119], v[144:147], v[186:189], v[116:119]
	v_mfma_f32_16x16x32_bf16 v[116:119], v[148:151], v[190:193], v[116:119]
	v_mfma_f32_16x16x32_bf16 v[112:115], v[178:181], v[186:189], v[112:115]
	v_mfma_f32_16x16x32_bf16 v[112:115], v[182:185], v[190:193], v[112:115]
	v_mfma_f32_16x16x32_bf16 v[100:103], v[144:147], v[194:197], v[100:103]
	v_mfma_f32_16x16x32_bf16 v[100:103], v[148:151], v[198:201], v[100:103]
	v_mfma_f32_16x16x32_bf16 v[96:99], v[178:181], v[194:197], v[96:99]
	v_mfma_f32_16x16x32_bf16 v[96:99], v[182:185], v[198:201], v[96:99]
	v_mfma_f32_16x16x32_bf16 v[84:87], v[144:147], v[202:205], v[84:87]
	v_mfma_f32_16x16x32_bf16 v[84:87], v[148:151], v[206:209], v[84:87]
	v_mfma_f32_16x16x32_bf16 v[80:83], v[178:181], v[202:205], v[80:83]
	v_mfma_f32_16x16x32_bf16 v[80:83], v[182:185], v[206:209], v[80:83]
	v_mfma_f32_16x16x32_bf16 v[68:71], v[144:147], v[210:213], v[68:71]
	v_mfma_f32_16x16x32_bf16 v[68:71], v[148:151], v[214:217], v[68:71]
	v_mfma_f32_16x16x32_bf16 v[64:67], v[178:181], v[210:213], v[64:67]
	v_mfma_f32_16x16x32_bf16 v[64:67], v[182:185], v[214:217], v[64:67]
	s_setprio 0
	s_barrier
; #define PG8_STAGE(bufoff, gbase, voff) do { _Pragma("unroll") for (int _i = 0; _i < 2; ++_i) \
;         __builtin_amdgcn_global_load_lds((const unsigned*)((const char*)(gbase) + (voff)[_i]), (PG8_LAS unsigned*)(lds + (bufoff) + ldsw + _i * 8192), 16, 0, 0); } while (0)
; #define PG8_LDA(dst, b, h) do { _Pragma("unroll") for (int m = 0; m < 4; ++m) _Pragma("unroll") for (int k = 0; k < 2; ++k) dst[m][k] = *(const PG8_LAS bf16x8*)(lds + PG8_SA(b, h) + aoff + m * 2048 + k * 1024); } while (0)
; #define PG8_MMA(ai, bj, At, Bt) do { __builtin_amdgcn_s_setprio(1); _Pragma("unroll") for (int m = 0; m < 4; ++m) _Pragma("unroll") for (int n = 0; n < 2; ++n) _Pragma("unroll") for (int k = 0; k < 2; ++k) \
;         acc[ai][bj][m][n] = __builtin_amdgcn_mfma_f32_16x16x32_bf16(Bt[n][k], At[m][k], acc[ai][bj][m][n], 0, 0, 0); __builtin_amdgcn_s_setprio(0); } while (0)
; #define PG8_WAIT_V(n) asm volatile("s_waitcnt vmcnt(" #n ")" ::: "memory")
; #define PG8_WAIT_L(n) asm volatile("s_waitcnt lgkmcnt(" #n ")" ::: "memory")
; #define PG8_BAR __builtin_amdgcn_s_barrier()
; #define PG8_SCHED __builtin_amdgcn_sched_barrier(0)
; template <class Epi, class Sched, bool ALIGN_EPI = false, bool SP2 = false>
; __device__ __forceinline__ void gemm_phase(PG8_LAS unsigned char* lds, const Gemm g, const Sched& S, const Epi& E) {
;     ...
;             PG8_LDA(At, 1, 1); PG8_STAGE(PG8_SB(1, 0), b3, voffB); PG8_STAGE(PG8_SB(1, 1), b3 + hstepB, voffB); PG8_STAGE(PG8_SA(1, 0), a3, voffA);
;             PG8_WAIT_V(8); PG8_WAIT_L(0); PG8_BAR; PG8_MMA(1, 0, At, B0); PG8_MMA(1, 1, At, B1); PG8_BAR; PG8_SCHED;
;     ...
;         if constexpr (ALIGN_EPI) { if (wr == 0) PG8_BAR; }
	s_nop 0
	s_add_u32 s42, s40, 0x8000
	s_addc_u32 s43, s41, 0
	s_add_i32 s64, s64, s20
	v_lshl_add_u64 v[172:173], s[42:43], 0, v[156:157]
	s_mov_b32 m0, s64
	ds_read_b128 v[186:189], v177 offset:49152
	ds_read_b128 v[190:193], v177 offset:50176
	ds_read_b128 v[194:197], v177 offset:51200
	ds_read_b128 v[198:201], v177 offset:52224
	ds_read_b128 v[202:205], v177 offset:53248
	ds_read_b128 v[206:209], v177 offset:54272
	ds_read_b128 v[210:213], v177 offset:55296
	ds_read_b128 v[214:217], v177 offset:56320
	global_load_lds_dwordx4 v[172:173], off
	s_add_i32 m0, s64, 0x2000
	s_add_u32 s40, s40, 0xc000
	v_lshl_add_u64 v[172:173], s[42:43], 0, v[152:153]
	s_addc_u32 s41, s41, 0
	s_add_i32 s42, s65, s20
	global_load_lds_dwordx4 v[172:173], off
	v_lshl_add_u64 v[172:173], s[40:41], 0, v[156:157]
	s_mov_b32 m0, s42
	s_nop 0
	global_load_lds_dwordx4 v[172:173], off
	v_lshl_add_u64 v[172:173], s[40:41], 0, v[152:153]
	s_add_i32 m0, s42, 0x2000
	s_nop 0
	global_load_lds_dwordx4 v[172:173], off
	v_lshl_add_u64 v[172:173], s[38:39], 0, v[158:159]
	s_mov_b32 m0, s29
	s_nop 0
	global_load_lds_dwordx4 v[172:173], off
	v_lshl_add_u64 v[172:173], s[38:39], 0, v[154:155]
	s_mov_b32 m0, s30
	s_nop 0
	global_load_lds_dwordx4 v[172:173], off
	s_waitcnt vmcnt(8)
	s_waitcnt lgkmcnt(0)
	s_barrier
	s_setprio 1
	s_waitcnt lgkmcnt(0)
	v_mfma_f32_16x16x32_bf16 v[60:63], v[128:131], v[186:189], v[60:63]
	v_mfma_f32_16x16x32_bf16 v[60:63], v[132:135], v[190:193], v[60:63]
	v_mfma_f32_16x16x32_bf16 v[56:59], v[136:139], v[186:189], v[56:59]
	v_mfma_f32_16x16x32_bf16 v[56:59], v[140:143], v[190:193], v[56:59]
	v_mfma_f32_16x16x32_bf16 v[44:47], v[128:131], v[194:197], v[44:47]
	v_mfma_f32_16x16x32_bf16 v[44:47], v[132:135], v[198:201], v[44:47]
	v_mfma_f32_16x16x32_bf16 v[40:43], v[136:139], v[194:197], v[40:43]
	v_mfma_f32_16x16x32_bf16 v[40:43], v[140:143], v[198:201], v[40:43]
	v_mfma_f32_16x16x32_bf16 v[28:31], v[128:131], v[202:205], v[28:31]
	v_mfma_f32_16x16x32_bf16 v[28:31], v[132:135], v[206:209], v[28:31]
	v_mfma_f32_16x16x32_bf16 v[24:27], v[136:139], v[202:205], v[24:27]
	v_mfma_f32_16x16x32_bf16 v[24:27], v[140:143], v[206:209], v[24:27]
	v_mfma_f32_16x16x32_bf16 v[12:15], v[128:131], v[210:213], v[12:15]
	v_mfma_f32_16x16x32_bf16 v[12:15], v[132:135], v[214:217], v[12:15]
	v_mfma_f32_16x16x32_bf16 v[8:11], v[136:139], v[210:213], v[8:11]
	v_mfma_f32_16x16x32_bf16 v[8:11], v[140:143], v[214:217], v[8:11]
	s_setprio 0
	s_setprio 1
	v_mfma_f32_16x16x32_bf16 v[52:55], v[144:147], v[186:189], v[52:55]
	v_mfma_f32_16x16x32_bf16 v[52:55], v[148:151], v[190:193], v[52:55]
	v_mfma_f32_16x16x32_bf16 v[48:51], v[178:181], v[186:189], v[48:51]
	v_mfma_f32_16x16x32_bf16 v[48:51], v[182:185], v[190:193], v[48:51]
	v_mfma_f32_16x16x32_bf16 v[36:39], v[144:147], v[194:197], v[36:39]
	v_mfma_f32_16x16x32_bf16 v[36:39], v[148:151], v[198:201], v[36:39]
	v_mfma_f32_16x16x32_bf16 v[32:35], v[178:181], v[194:197], v[32:35]
	v_mfma_f32_16x16x32_bf16 v[32:35], v[182:185], v[198:201], v[32:35]
	v_mfma_f32_16x16x32_bf16 v[20:23], v[144:147], v[202:205], v[20:23]
	v_mfma_f32_16x16x32_bf16 v[20:23], v[148:151], v[206:209], v[20:23]
	v_mfma_f32_16x16x32_bf16 v[16:19], v[178:181], v[202:205], v[16:19]
	v_mfma_f32_16x16x32_bf16 v[16:19], v[182:185], v[206:209], v[16:19]
	v_mfma_f32_16x16x32_bf16 v[4:7], v[144:147], v[210:213], v[4:7]
	v_mfma_f32_16x16x32_bf16 v[4:7], v[148:151], v[214:217], v[4:7]
	v_mfma_f32_16x16x32_bf16 v[0:3], v[178:181], v[210:213], v[0:3]
	v_mfma_f32_16x16x32_bf16 v[0:3], v[182:185], v[214:217], v[0:3]
	s_setprio 0
	s_barrier
	s_add_u32 s36, s36, 0x10000
	s_addc_u32 s37, s37, 0
	s_add_u32 s78, s78, 0x10000
	s_addc_u32 s82, s82, 0
	s_cmp_ge_u32 s84, s26
	s_mov_b32 s38, s84
	s_cbranch_scc0 .LBB0_193
	s_and_b64 vcc, exec, s[60:61]
	s_cbranch_vccz .LBB0_196
	s_barrier

; #define PG8_STAGE(bufoff, gbase, voff) do { _Pragma("unroll") for (int _i = 0; _i < 2; ++_i) \
;         __builtin_amdgcn_global_load_lds((const unsigned*)((const char*)(gbase) + (voff)[_i]), (PG8_LAS unsigned*)(lds + (bufoff) + ldsw + _i * 8192), 16, 0, 0); } while (0)
; #define PG8_LDA(dst, b, h) do { _Pragma("unroll") for (int m = 0; m < 4; ++m) _Pragma("unroll") for (int k = 0; k < 2; ++k) dst[m][k] = *(const PG8_LAS bf16x8*)(lds + PG8_SA(b, h) + aoff + m * 2048 + k * 1024); } while (0)
; #define PG8_LDB(dst, b, h) do { _Pragma("unroll") for (int n = 0; n < 2; ++n) _Pragma("unroll") for (int k = 0; k < 2; ++k) dst[n][k] = *(const PG8_LAS bf16x8*)(lds + PG8_SB(b, h) + boff + n * 2048 + k * 1024); } while (0)
; #define PG8_MMA(ai, bj, At, Bt) do { __builtin_amdgcn_s_setprio(1); _Pragma("unroll") for (int m = 0; m < 4; ++m) _Pragma("unroll") for (int n = 0; n < 2; ++n) _Pragma("unroll") for (int k = 0; k < 2; ++k) \
;         acc[ai][bj][m][n] = __builtin_amdgcn_mfma_f32_16x16x32_bf16(Bt[n][k], At[m][k], acc[ai][bj][m][n], 0, 0, 0); __builtin_amdgcn_s_setprio(0); } while (0)
; #define PG8_WAIT_V(n) asm volatile("s_waitcnt vmcnt(" #n ")" ::: "memory")
; #define PG8_WAIT_L(n) asm volatile("s_waitcnt lgkmcnt(" #n ")" ::: "memory")
; #define PG8_BAR __builtin_amdgcn_s_barrier()
; #define PG8_SCHED __builtin_amdgcn_sched_barrier(0)
; template <class Epi, class Sched, bool ALIGN_EPI = false, bool SP2 = false>
; __device__ __forceinline__ void gemm_phase(PG8_LAS unsigned char* lds, const Gemm g, const Sched& S, const Epi& E) {
;     ...
;             const bool last = (t == nt - 2);
;             const char* a1 = cA + (size_t)(t + 1) * kstepB;
;             const char* a2 = last ? nA : cA + (size_t)(t + 2) * kstepB; const char* b2 = last ? nB : cB + (size_t)(t + 2) * kstepB;
;             const char* a3 = a2 + kstepB; const char* b3 = b2 + kstepB;
;             if (last && has_next) S.a_ready(nxt);
;             if constexpr (SP2) {
;             PG8_LDB(B0, 0, 0); PG8_LDB(B1, 0, 1); PG8_SCHED; PG8_LDA(At, 0, 0); PG8_STAGE(PG8_SA(1, 1), a1 + hstepB, voffA);
;             PG8_WAIT_V(8); PG8_WAIT_L(0); PG8_BAR; PG8_MMA(0, 0, At, B0); PG8_MMA(0, 1, At, B1); PG8_BAR; PG8_SCHED;
;             PG8_LDA(At, 0, 1); PG8_STAGE(PG8_SB(0, 0), b2, voffB); PG8_STAGE(PG8_SB(0, 1), b2 + hstepB, voffB); PG8_STAGE(PG8_SA(0, 0), a2, voffA);
.LBB0_232:
	s_add_u32 s31, s36, 0x4000
	s_addc_u32 s38, s37, 0
	s_cmp_eq_u32 s30, 28
	s_cselect_b32 s42, s26, s31
	s_cselect_b32 s43, s13, s38
	s_cselect_b32 s40, s27, s28
	s_cselect_b32 s41, s11, s29
	s_add_u32 s38, s42, 0x8000
	s_addc_u32 s39, s43, 0
	s_add_i32 s31, 0, 0x10000
	s_add_i32 s60, 0, 0x14000
	v_add_u32_e32 v152, s31, v169
	v_add_u32_e32 v175, s60, v169
	ds_read_b128 v[128:131], v152
	ds_read_b128 v[132:135], v152 offset:1024
	ds_read_b128 v[148:151], v152 offset:2048
	ds_read_b128 v[152:155], v152 offset:3072
	ds_read_b128 v[156:159], v175
	ds_read_b128 v[160:163], v175 offset:1024
	ds_read_b128 v[164:167], v175 offset:2048
	ds_read_b128 v[176:179], v175 offset:3072
	v_lshl_add_u64 v[212:213], s[36:37], 0, v[144:145]
	s_add_i32 m0, s17, 0xc000
	ds_read_b128 v[180:183], v174
	ds_read_b128 v[184:187], v174 offset:1024
	ds_read_b128 v[188:191], v174 offset:2048
	ds_read_b128 v[192:195], v174 offset:3072
	ds_read_b128 v[196:199], v174 offset:4096
	ds_read_b128 v[200:203], v174 offset:5120
	ds_read_b128 v[204:207], v174 offset:6144
	ds_read_b128 v[208:211], v174 offset:7168
	global_load_lds_dwordx4 v[212:213], off
	v_lshl_add_u64 v[212:213], s[36:37], 0, v[146:147]
	s_add_i32 m0, s17, 0xe000
	s_nop 0
	global_load_lds_dwordx4 v[212:213], off
	s_waitcnt vmcnt(8)
	s_waitcnt lgkmcnt(0)
	s_barrier
	s_setprio 1
	s_waitcnt lgkmcnt(0)
	v_mfma_f32_16x16x32_bf16 v[124:127], v[128:131], v[180:183], v[124:127]
	v_mfma_f32_16x16x32_bf16 v[124:127], v[132:135], v[184:187], v[124:127]
	v_mfma_f32_16x16x32_bf16 v[120:123], v[148:151], v[180:183], v[120:123]
	v_mfma_f32_16x16x32_bf16 v[120:123], v[152:155], v[184:187], v[120:123]
	v_mfma_f32_16x16x32_bf16 v[108:111], v[128:131], v[188:191], v[108:111]
	v_mfma_f32_16x16x32_bf16 v[108:111], v[132:135], v[192:195], v[108:111]
	v_mfma_f32_16x16x32_bf16 v[104:107], v[148:151], v[188:191], v[104:107]
	v_mfma_f32_16x16x32_bf16 v[104:107], v[152:155], v[192:195], v[104:107]
	v_mfma_f32_16x16x32_bf16 v[92:95], v[128:131], v[196:199], v[92:95]
	v_mfma_f32_16x16x32_bf16 v[92:95], v[132:135], v[200:203], v[92:95]
	v_mfma_f32_16x16x32_bf16 v[88:91], v[148:151], v[196:199], v[88:91]
	v_mfma_f32_16x16x32_bf16 v[88:91], v[152:155], v[200:203], v[88:91]
	v_mfma_f32_16x16x32_bf16 v[76:79], v[128:131], v[204:207], v[76:79]
	v_mfma_f32_16x16x32_bf16 v[76:79], v[132:135], v[208:211], v[76:79]
	v_mfma_f32_16x16x32_bf16 v[72:75], v[148:151], v[204:207], v[72:75]
	v_mfma_f32_16x16x32_bf16 v[72:75], v[152:155], v[208:211], v[72:75]
	s_setprio 0
	s_setprio 1
	v_mfma_f32_16x16x32_bf16 v[116:119], v[156:159], v[180:183], v[116:119]
	v_mfma_f32_16x16x32_bf16 v[116:119], v[160:163], v[184:187], v[116:119]
	v_mfma_f32_16x16x32_bf16 v[112:115], v[164:167], v[180:183], v[112:115]
	v_mfma_f32_16x16x32_bf16 v[112:115], v[176:179], v[184:187], v[112:115]
	v_mfma_f32_16x16x32_bf16 v[100:103], v[156:159], v[188:191], v[100:103]
	v_mfma_f32_16x16x32_bf16 v[100:103], v[160:163], v[192:195], v[100:103]
	v_mfma_f32_16x16x32_bf16 v[96:99], v[164:167], v[188:191], v[96:99]
	v_mfma_f32_16x16x32_bf16 v[96:99], v[176:179], v[192:195], v[96:99]
	v_mfma_f32_16x16x32_bf16 v[84:87], v[156:159], v[196:199], v[84:87]
	v_mfma_f32_16x16x32_bf16 v[84:87], v[160:163], v[200:203], v[84:87]
	v_mfma_f32_16x16x32_bf16 v[80:83], v[164:167], v[196:199], v[80:83]
	v_mfma_f32_16x16x32_bf16 v[80:83], v[176:179], v[200:203], v[80:83]
	v_mfma_f32_16x16x32_bf16 v[68:71], v[156:159], v[204:207], v[68:71]
	v_mfma_f32_16x16x32_bf16 v[68:71], v[160:163], v[208:211], v[68:71]
	v_mfma_f32_16x16x32_bf16 v[64:67], v[164:167], v[204:207], v[64:67]
	v_mfma_f32_16x16x32_bf16 v[64:67], v[176:179], v[208:211], v[64:67]
	s_setprio 0
	s_barrier
	s_add_i32 s31, s31, s14
	v_lshl_add_u64 v[212:213], s[40:41], 0, v[220:221]
	s_mov_b32 m0, s31
	ds_read_b128 v[180:183], v174 offset:16384
	ds_read_b128 v[184:187], v174 offset:17408
	ds_read_b128 v[188:191], v174 offset:18432
	ds_read_b128 v[192:195], v174 offset:19456
	ds_read_b128 v[196:199], v174 offset:20480
	ds_read_b128 v[200:203], v174 offset:21504
	ds_read_b128 v[204:207], v174 offset:22528
	ds_read_b128 v[208:211], v174 offset:23552
	global_load_lds_dwordx4 v[212:213], off
	s_add_i32 m0, s31, 0x2000
	s_add_u32 s44, s40, 0x4000
	v_lshl_add_u64 v[212:213], s[40:41], 0, v[136:137]
	s_addc_u32 s45, s41, 0
	s_add_i32 s31, s60, s14
	global_load_lds_dwordx4 v[212:213], off
	v_lshl_add_u64 v[212:213], s[44:45], 0, v[220:221]
	s_mov_b32 m0, s31
	s_nop 0
	global_load_lds_dwordx4 v[212:213], off
	v_lshl_add_u64 v[212:213], s[44:45], 0, v[136:137]
	s_add_i32 m0, s31, 0x2000
	s_nop 0
	global_load_lds_dwordx4 v[212:213], off
	v_lshl_add_u64 v[212:213], s[42:43], 0, v[140:141]
	s_mov_b32 m0, s17
	s_nop 0
	global_load_lds_dwordx4 v[212:213], off
	v_lshl_add_u64 v[212:213], s[42:43], 0, v[138:139]
	s_mov_b32 m0, s18
	s_nop 0
	global_load_lds_dwordx4 v[212:213], off
	s_waitcnt vmcnt(8)
	s_waitcnt lgkmcnt(0)
	s_barrier
; #define PG8_STAGE(bufoff, gbase, voff) do { _Pragma("unroll") for (int _i = 0; _i < 2; ++_i) \
;         __builtin_amdgcn_global_load_lds((const unsigned*)((const char*)(gbase) + (voff)[_i]), (PG8_LAS unsigned*)(lds + (bufoff) + ldsw + _i * 8192), 16, 0, 0); } while (0)
; #define PG8_LDA(dst, b, h) do { _Pragma("unroll") for (int m = 0; m < 4; ++m) _Pragma("unroll") for (int k = 0; k < 2; ++k) dst[m][k] = *(const PG8_LAS bf16x8*)(lds + PG8_SA(b, h) + aoff + m * 2048 + k * 1024); } while (0)
; #define PG8_LDB(dst, b, h) do { _Pragma("unroll") for (int n = 0; n < 2; ++n) _Pragma("unroll") for (int k = 0; k < 2; ++k) dst[n][k] = *(const PG8_LAS bf16x8*)(lds + PG8_SB(b, h) + boff + n * 2048 + k * 1024); } while (0)
; #define PG8_MMA(ai, bj, At, Bt) do { __builtin_amdgcn_s_setprio(1); _Pragma("unroll") for (int m = 0; m < 4; ++m) _Pragma("unroll") for (int n = 0; n < 2; ++n) _Pragma("unroll") for (int k = 0; k < 2; ++k) \
;         acc[ai][bj][m][n] = __builtin_amdgcn_mfma_f32_16x16x32_bf16(Bt[n][k], At[m][k], acc[ai][bj][m][n], 0, 0, 0); __builtin_amdgcn_s_setprio(0); } while (0)
; #define PG8_WAIT_V(n) asm volatile("s_waitcnt vmcnt(" #n ")" ::: "memory")
; #define PG8_WAIT_L(n) asm volatile("s_waitcnt lgkmcnt(" #n ")" ::: "memory")
; #define PG8_BAR __builtin_amdgcn_s_barrier()
; #define PG8_SCHED __builtin_amdgcn_sched_barrier(0)
; template <class Epi, class Sched, bool ALIGN_EPI = false, bool SP2 = false>
; __device__ __forceinline__ void gemm_phase(PG8_LAS unsigned char* lds, const Gemm g, const Sched& S, const Epi& E) {
;     ...
;             PG8_WAIT_V(8); PG8_WAIT_L(0); PG8_BAR; PG8_MMA(1, 0, At, B0); PG8_MMA(1, 1, At, B1); PG8_BAR; PG8_SCHED;
;             PG8_LDB(B0, 1, 0); PG8_LDB(B1, 1, 1); PG8_SCHED; PG8_LDA(At, 1, 0); PG8_STAGE(PG8_SA(0, 1), a2 + hstepB, voffA);
;             PG8_WAIT_V(8); PG8_WAIT_L(0); PG8_BAR; PG8_MMA(0, 0, At, B0); PG8_MMA(0, 1, At, B1); PG8_BAR; PG8_SCHED;
	s_setprio 1
	s_waitcnt lgkmcnt(0)
	v_mfma_f32_16x16x32_bf16 v[60:63], v[128:131], v[180:183], v[60:63]
	v_mfma_f32_16x16x32_bf16 v[60:63], v[132:135], v[184:187], v[60:63]
	v_mfma_f32_16x16x32_bf16 v[56:59], v[148:151], v[180:183], v[56:59]
	v_mfma_f32_16x16x32_bf16 v[56:59], v[152:155], v[184:187], v[56:59]
	v_mfma_f32_16x16x32_bf16 v[48:51], v[128:131], v[188:191], v[48:51]
	v_mfma_f32_16x16x32_bf16 v[48:51], v[132:135], v[192:195], v[48:51]
	v_mfma_f32_16x16x32_bf16 v[40:43], v[148:151], v[188:191], v[40:43]
	v_mfma_f32_16x16x32_bf16 v[40:43], v[152:155], v[192:195], v[40:43]
	v_mfma_f32_16x16x32_bf16 v[32:35], v[128:131], v[196:199], v[32:35]
	v_mfma_f32_16x16x32_bf16 v[32:35], v[132:135], v[200:203], v[32:35]
	v_mfma_f32_16x16x32_bf16 v[24:27], v[148:151], v[196:199], v[24:27]
	v_mfma_f32_16x16x32_bf16 v[24:27], v[152:155], v[200:203], v[24:27]
	v_mfma_f32_16x16x32_bf16 v[16:19], v[128:131], v[204:207], v[16:19]
	v_mfma_f32_16x16x32_bf16 v[16:19], v[132:135], v[208:211], v[16:19]
	v_mfma_f32_16x16x32_bf16 v[8:11], v[148:151], v[204:207], v[8:11]
	v_mfma_f32_16x16x32_bf16 v[8:11], v[152:155], v[208:211], v[8:11]
	s_setprio 0
	s_setprio 1
	v_mfma_f32_16x16x32_bf16 v[52:55], v[156:159], v[180:183], v[52:55]
	v_mfma_f32_16x16x32_bf16 v[52:55], v[160:163], v[184:187], v[52:55]
	v_mfma_f32_16x16x32_bf16 v[44:47], v[164:167], v[180:183], v[44:47]
	v_mfma_f32_16x16x32_bf16 v[44:47], v[176:179], v[184:187], v[44:47]
	v_mfma_f32_16x16x32_bf16 v[36:39], v[156:159], v[188:191], v[36:39]
	v_mfma_f32_16x16x32_bf16 v[36:39], v[160:163], v[192:195], v[36:39]
	v_mfma_f32_16x16x32_bf16 v[28:31], v[164:167], v[188:191], v[28:31]
	v_mfma_f32_16x16x32_bf16 v[28:31], v[176:179], v[192:195], v[28:31]
	v_mfma_f32_16x16x32_bf16 v[20:23], v[156:159], v[196:199], v[20:23]
	v_mfma_f32_16x16x32_bf16 v[20:23], v[160:163], v[200:203], v[20:23]
	v_mfma_f32_16x16x32_bf16 v[12:15], v[164:167], v[196:199], v[12:15]
	v_mfma_f32_16x16x32_bf16 v[12:15], v[176:179], v[200:203], v[12:15]
	v_mfma_f32_16x16x32_bf16 v[4:7], v[156:159], v[204:207], v[4:7]
	v_mfma_f32_16x16x32_bf16 v[4:7], v[160:163], v[208:211], v[4:7]
	v_mfma_f32_16x16x32_bf16 v[0:3], v[164:167], v[204:207], v[0:3]
	v_mfma_f32_16x16x32_bf16 v[0:3], v[176:179], v[208:211], v[0:3]
	s_setprio 0
	s_barrier
	s_add_i32 s31, 0, 0x18000
	s_add_i32 s44, 0, 0x1c000
	v_add_u32_e32 v152, s31, v169
	v_add_u32_e32 v175, s44, v169
	ds_read_b128 v[128:131], v152
	ds_read_b128 v[132:135], v152 offset:1024
	ds_read_b128 v[148:151], v152 offset:2048
	ds_read_b128 v[152:155], v152 offset:3072
	ds_read_b128 v[156:159], v175
	ds_read_b128 v[160:163], v175 offset:1024
	ds_read_b128 v[164:167], v175 offset:2048
	ds_read_b128 v[176:179], v175 offset:3072
	s_add_u32 s42, s42, 0x4000
	s_addc_u32 s43, s43, 0
	s_mov_b32 m0, s19
	v_lshl_add_u64 v[212:213], s[42:43], 0, v[140:141]
	ds_read_b128 v[180:183], v174 offset:32768
	ds_read_b128 v[184:187], v174 offset:33792
	ds_read_b128 v[188:191], v174 offset:34816
	ds_read_b128 v[192:195], v174 offset:35840
	ds_read_b128 v[196:199], v174 offset:36864
	ds_read_b128 v[200:203], v174 offset:37888
	ds_read_b128 v[204:207], v174 offset:38912
	ds_read_b128 v[208:211], v174 offset:39936
	global_load_lds_dwordx4 v[212:213], off
	v_lshl_add_u64 v[212:213], s[42:43], 0, v[138:139]
	s_mov_b32 m0, s20
	s_nop 0
	global_load_lds_dwordx4 v[212:213], off
	s_nop 0
	s_waitcnt vmcnt(8)
	s_waitcnt lgkmcnt(0)
	s_barrier
	s_setprio 1
	s_waitcnt lgkmcnt(0)
	v_mfma_f32_16x16x32_bf16 v[124:127], v[128:131], v[180:183], v[124:127]
	v_mfma_f32_16x16x32_bf16 v[124:127], v[132:135], v[184:187], v[124:127]
	v_mfma_f32_16x16x32_bf16 v[120:123], v[148:151], v[180:183], v[120:123]
	v_mfma_f32_16x16x32_bf16 v[120:123], v[152:155], v[184:187], v[120:123]
	v_mfma_f32_16x16x32_bf16 v[108:111], v[128:131], v[188:191], v[108:111]
	v_mfma_f32_16x16x32_bf16 v[108:111], v[132:135], v[192:195], v[108:111]
	v_mfma_f32_16x16x32_bf16 v[104:107], v[148:151], v[188:191], v[104:107]
	v_mfma_f32_16x16x32_bf16 v[104:107], v[152:155], v[192:195], v[104:107]
	v_mfma_f32_16x16x32_bf16 v[92:95], v[128:131], v[196:199], v[92:95]
	v_mfma_f32_16x16x32_bf16 v[92:95], v[132:135], v[200:203], v[92:95]
	v_mfma_f32_16x16x32_bf16 v[88:91], v[148:151], v[196:199], v[88:91]
	v_mfma_f32_16x16x32_bf16 v[88:91], v[152:155], v[200:203], v[88:91]
	v_mfma_f32_16x16x32_bf16 v[76:79], v[128:131], v[204:207], v[76:79]
	v_mfma_f32_16x16x32_bf16 v[76:79], v[132:135], v[208:211], v[76:79]
	v_mfma_f32_16x16x32_bf16 v[72:75], v[148:151], v[204:207], v[72:75]
	v_mfma_f32_16x16x32_bf16 v[72:75], v[152:155], v[208:211], v[72:75]
	s_setprio 0
	s_setprio 1
	v_mfma_f32_16x16x32_bf16 v[116:119], v[156:159], v[180:183], v[116:119]
	v_mfma_f32_16x16x32_bf16 v[116:119], v[160:163], v[184:187], v[116:119]
	v_mfma_f32_16x16x32_bf16 v[112:115], v[164:167], v[180:183], v[112:115]
	v_mfma_f32_16x16x32_bf16 v[112:115], v[176:179], v[184:187], v[112:115]
	v_mfma_f32_16x16x32_bf16 v[100:103], v[156:159], v[188:191], v[100:103]
	v_mfma_f32_16x16x32_bf16 v[100:103], v[160:163], v[192:195], v[100:103]
	v_mfma_f32_16x16x32_bf16 v[96:99], v[164:167], v[188:191], v[96:99]
	v_mfma_f32_16x16x32_bf16 v[96:99], v[176:179], v[192:195], v[96:99]
	v_mfma_f32_16x16x32_bf16 v[84:87], v[156:159], v[196:199], v[84:87]
	v_mfma_f32_16x16x32_bf16 v[84:87], v[160:163], v[200:203], v[84:87]
	v_mfma_f32_16x16x32_bf16 v[80:83], v[164:167], v[196:199], v[80:83]
	v_mfma_f32_16x16x32_bf16 v[80:83], v[176:179], v[200:203], v[80:83]
	v_mfma_f32_16x16x32_bf16 v[68:71], v[156:159], v[204:207], v[68:71]
	v_mfma_f32_16x16x32_bf16 v[68:71], v[160:163], v[208:211], v[68:71]
	v_mfma_f32_16x16x32_bf16 v[64:67], v[164:167], v[204:207], v[64:67]
	v_mfma_f32_16x16x32_bf16 v[64:67], v[176:179], v[208:211], v[64:67]
	s_setprio 0
	s_barrier
; #define PG8_STAGE(bufoff, gbase, voff) do { _Pragma("unroll") for (int _i = 0; _i < 2; ++_i) \
;         __builtin_amdgcn_global_load_lds((const unsigned*)((const char*)(gbase) + (voff)[_i]), (PG8_LAS unsigned*)(lds + (bufoff) + ldsw + _i * 8192), 16, 0, 0); } while (0)
; #define PG8_LDA(dst, b, h) do { _Pragma("unroll") for (int m = 0; m < 4; ++m) _Pragma("unroll") for (int k = 0; k < 2; ++k) dst[m][k] = *(const PG8_LAS bf16x8*)(lds + PG8_SA(b, h) + aoff + m * 2048 + k * 1024); } while (0)
; #define PG8_MMA(ai, bj, At, Bt) do { __builtin_amdgcn_s_setprio(1); _Pragma("unroll") for (int m = 0; m < 4; ++m) _Pragma("unroll") for (int n = 0; n < 2; ++n) _Pragma("unroll") for (int k = 0; k < 2; ++k) \
;         acc[ai][bj][m][n] = __builtin_amdgcn_mfma_f32_16x16x32_bf16(Bt[n][k], At[m][k], acc[ai][bj][m][n], 0, 0, 0); __builtin_amdgcn_s_setprio(0); } while (0)
; #define PG8_WAIT_V(n) asm volatile("s_waitcnt vmcnt(" #n ")" ::: "memory")
; #define PG8_WAIT_L(n) asm volatile("s_waitcnt lgkmcnt(" #n ")" ::: "memory")
; #define PG8_BAR __builtin_amdgcn_s_barrier()
; #define PG8_SCHED __builtin_amdgcn_sched_barrier(0)
; template <class Epi, class Sched, bool ALIGN_EPI = false, bool SP2 = false>
; __device__ __forceinline__ void gemm_phase(PG8_LAS unsigned char* lds, const Gemm g, const Sched& S, const Epi& E) {
;     ...
;             PG8_LDA(At, 1, 1); PG8_STAGE(PG8_SB(1, 0), b3, voffB); PG8_STAGE(PG8_SB(1, 1), b3 + hstepB, voffB); PG8_STAGE(PG8_SA(1, 0), a3, voffA);
;             PG8_WAIT_V(8); PG8_WAIT_L(0); PG8_BAR; PG8_MMA(1, 0, At, B0); PG8_MMA(1, 1, At, B1); PG8_BAR; PG8_SCHED;
;     ...
;         if constexpr (ALIGN_EPI) { if (wr == 0) PG8_BAR; }
	s_nop 0
	s_add_u32 s42, s40, 0x8000
	s_addc_u32 s43, s41, 0
	s_add_i32 s31, s31, s14
	v_lshl_add_u64 v[212:213], s[42:43], 0, v[220:221]
	s_mov_b32 m0, s31
	ds_read_b128 v[180:183], v174 offset:49152
	ds_read_b128 v[184:187], v174 offset:50176
	ds_read_b128 v[188:191], v174 offset:51200
	ds_read_b128 v[192:195], v174 offset:52224
	ds_read_b128 v[196:199], v174 offset:53248
	ds_read_b128 v[200:203], v174 offset:54272
	ds_read_b128 v[204:207], v174 offset:55296
	ds_read_b128 v[208:211], v174 offset:56320
	global_load_lds_dwordx4 v[212:213], off
	s_add_i32 m0, s31, 0x2000
	s_add_u32 s40, s40, 0xc000
	v_lshl_add_u64 v[212:213], s[42:43], 0, v[136:137]
	s_addc_u32 s41, s41, 0
	s_add_i32 s31, s44, s14
	global_load_lds_dwordx4 v[212:213], off
	v_lshl_add_u64 v[212:213], s[40:41], 0, v[220:221]
	s_mov_b32 m0, s31
	s_nop 0
	global_load_lds_dwordx4 v[212:213], off
	v_lshl_add_u64 v[212:213], s[40:41], 0, v[136:137]
	s_add_i32 m0, s31, 0x2000
	s_nop 0
	global_load_lds_dwordx4 v[212:213], off
	v_lshl_add_u64 v[212:213], s[38:39], 0, v[140:141]
	s_mov_b32 m0, s21
	s_nop 0
	global_load_lds_dwordx4 v[212:213], off
	v_lshl_add_u64 v[212:213], s[38:39], 0, v[138:139]
	s_mov_b32 m0, s22
	s_nop 0
	global_load_lds_dwordx4 v[212:213], off
	s_waitcnt vmcnt(8)
	s_waitcnt lgkmcnt(0)
	s_barrier
	s_setprio 1
	s_waitcnt lgkmcnt(0)
	v_mfma_f32_16x16x32_bf16 v[60:63], v[128:131], v[180:183], v[60:63]
	v_mfma_f32_16x16x32_bf16 v[60:63], v[132:135], v[184:187], v[60:63]
	v_mfma_f32_16x16x32_bf16 v[56:59], v[148:151], v[180:183], v[56:59]
	v_mfma_f32_16x16x32_bf16 v[56:59], v[152:155], v[184:187], v[56:59]
	v_mfma_f32_16x16x32_bf16 v[48:51], v[128:131], v[188:191], v[48:51]
	v_mfma_f32_16x16x32_bf16 v[48:51], v[132:135], v[192:195], v[48:51]
	v_mfma_f32_16x16x32_bf16 v[40:43], v[148:151], v[188:191], v[40:43]
	v_mfma_f32_16x16x32_bf16 v[40:43], v[152:155], v[192:195], v[40:43]
	v_mfma_f32_16x16x32_bf16 v[32:35], v[128:131], v[196:199], v[32:35]
	v_mfma_f32_16x16x32_bf16 v[32:35], v[132:135], v[200:203], v[32:35]
	v_mfma_f32_16x16x32_bf16 v[24:27], v[148:151], v[196:199], v[24:27]
	v_mfma_f32_16x16x32_bf16 v[24:27], v[152:155], v[200:203], v[24:27]
	v_mfma_f32_16x16x32_bf16 v[16:19], v[128:131], v[204:207], v[16:19]
	v_mfma_f32_16x16x32_bf16 v[16:19], v[132:135], v[208:211], v[16:19]
	v_mfma_f32_16x16x32_bf16 v[8:11], v[148:151], v[204:207], v[8:11]
	v_mfma_f32_16x16x32_bf16 v[8:11], v[152:155], v[208:211], v[8:11]
	s_setprio 0
	s_setprio 1
	v_mfma_f32_16x16x32_bf16 v[52:55], v[156:159], v[180:183], v[52:55]
	v_mfma_f32_16x16x32_bf16 v[52:55], v[160:163], v[184:187], v[52:55]
	v_mfma_f32_16x16x32_bf16 v[44:47], v[164:167], v[180:183], v[44:47]
	v_mfma_f32_16x16x32_bf16 v[44:47], v[176:179], v[184:187], v[44:47]
	v_mfma_f32_16x16x32_bf16 v[36:39], v[156:159], v[188:191], v[36:39]
	v_mfma_f32_16x16x32_bf16 v[36:39], v[160:163], v[192:195], v[36:39]
	v_mfma_f32_16x16x32_bf16 v[28:31], v[164:167], v[188:191], v[28:31]
	v_mfma_f32_16x16x32_bf16 v[28:31], v[176:179], v[192:195], v[28:31]
	v_mfma_f32_16x16x32_bf16 v[20:23], v[156:159], v[196:199], v[20:23]
	v_mfma_f32_16x16x32_bf16 v[20:23], v[160:163], v[200:203], v[20:23]
	v_mfma_f32_16x16x32_bf16 v[12:15], v[164:167], v[196:199], v[12:15]
	v_mfma_f32_16x16x32_bf16 v[12:15], v[176:179], v[200:203], v[12:15]
	v_mfma_f32_16x16x32_bf16 v[4:7], v[156:159], v[204:207], v[4:7]
	v_mfma_f32_16x16x32_bf16 v[4:7], v[160:163], v[208:211], v[4:7]
	v_mfma_f32_16x16x32_bf16 v[0:3], v[164:167], v[204:207], v[0:3]
	v_mfma_f32_16x16x32_bf16 v[0:3], v[176:179], v[208:211], v[0:3]
	s_setprio 0
	s_barrier
	s_add_i32 s30, s30, 2
	s_add_u32 s36, s36, 0x10000
	s_addc_u32 s37, s37, 0
	s_add_u32 s28, s28, 0x10000
	s_addc_u32 s29, s29, 0
	s_cmp_gt_u32 s30, 29
	s_cbranch_scc0 .LBB0_232
	s_and_b64 vcc, exec, s[8:9]
	s_cbranch_vccz .LBB0_235
	s_barrier

; #define PG8_STAGE(bufoff, gbase, voff) do { _Pragma("unroll") for (int _i = 0; _i < 2; ++_i) \
;         __builtin_amdgcn_global_load_lds((const unsigned*)((const char*)(gbase) + (voff)[_i]), (PG8_LAS unsigned*)(lds + (bufoff) + ldsw + _i * 8192), 16, 0, 0); } while (0)
; #define PG8_LDA(dst, b, h) do { _Pragma("unroll") for (int m = 0; m < 4; ++m) _Pragma("unroll") for (int k = 0; k < 2; ++k) dst[m][k] = *(const PG8_LAS bf16x8*)(lds + PG8_SA(b, h) + aoff + m * 2048 + k * 1024); } while (0)
; #define PG8_LDB(dst, b, h) do { _Pragma("unroll") for (int n = 0; n < 2; ++n) _Pragma("unroll") for (int k = 0; k < 2; ++k) dst[n][k] = *(const PG8_LAS bf16x8*)(lds + PG8_SB(b, h) + boff + n * 2048 + k * 1024); } while (0)
; #define PG8_MMA(ai, bj, At, Bt) do { __builtin_amdgcn_s_setprio(1); _Pragma("unroll") for (int m = 0; m < 4; ++m) _Pragma("unroll") for (int n = 0; n < 2; ++n) _Pragma("unroll") for (int k = 0; k < 2; ++k) \
;         acc[ai][bj][m][n] = __builtin_amdgcn_mfma_f32_16x16x32_bf16(Bt[n][k], At[m][k], acc[ai][bj][m][n], 0, 0, 0); __builtin_amdgcn_s_setprio(0); } while (0)
; #define PG8_WAIT_V(n) asm volatile("s_waitcnt vmcnt(" #n ")" ::: "memory")
; #define PG8_WAIT_L(n) asm volatile("s_waitcnt lgkmcnt(" #n ")" ::: "memory")
; #define PG8_BAR __builtin_amdgcn_s_barrier()
; #define PG8_SCHED __builtin_amdgcn_sched_barrier(0)
; template <class Epi, class Sched, bool ALIGN_EPI = false, bool SP2 = false>
; __device__ __forceinline__ void gemm_phase(PG8_LAS unsigned char* lds, const Gemm g, const Sched& S, const Epi& E) {
;     ...
;             const bool last = (t == nt - 2);
;             const char* a1 = cA + (size_t)(t + 1) * kstepB;
;             const char* a2 = last ? nA : cA + (size_t)(t + 2) * kstepB; const char* b2 = last ? nB : cB + (size_t)(t + 2) * kstepB;
;             const char* a3 = a2 + kstepB; const char* b3 = b2 + kstepB;
;             if (last && has_next) S.a_ready(nxt);
;             if constexpr (SP2) {
;             PG8_LDB(B0, 0, 0); PG8_LDB(B1, 0, 1); PG8_SCHED; PG8_LDA(At, 0, 0); PG8_STAGE(PG8_SA(1, 1), a1 + hstepB, voffA);
;             PG8_WAIT_V(8); PG8_WAIT_L(0); PG8_BAR; PG8_MMA(0, 0, At, B0); PG8_MMA(0, 1, At, B1); PG8_BAR; PG8_SCHED;
;             PG8_LDA(At, 0, 1); PG8_STAGE(PG8_SB(0, 0), b2, voffB); PG8_STAGE(PG8_SB(0, 1), b2 + hstepB, voffB); PG8_STAGE(PG8_SA(0, 0), a2, voffA);
.LBB0_263:
	s_add_u32 s38, s36, 0x4000
	s_addc_u32 s39, s37, 0
	s_cmp_eq_u32 s62, 28
	s_cselect_b32 s42, s30, s38
	s_cselect_b32 s43, s13, s39
	s_cselect_b32 s40, s31, s44
	s_cselect_b32 s41, s11, s45
	s_add_u32 s38, s42, 0x8000
	s_addc_u32 s39, s43, 0
	s_add_i32 s63, 0, 0x10000
	v_add_u32_e32 v151, s63, v165
	s_add_i32 s75, 0, 0x14000
	ds_read_b128 v[128:131], v151
	ds_read_b128 v[132:135], v151 offset:1024
	ds_read_b128 v[152:155], v151 offset:2048
	ds_read_b128 v[156:159], v151 offset:3072
	v_add_u32_e32 v151, s75, v165
	ds_read_b128 v[160:163], v151
	ds_read_b128 v[170:173], v151 offset:1024
	ds_read_b128 v[174:177], v151 offset:2048
	ds_read_b128 v[178:181], v151 offset:3072
	v_lshl_add_u64 v[214:215], s[36:37], 0, v[146:147]
	s_add_i32 m0, s19, 0xc000
	ds_read_b128 v[182:185], v168
	ds_read_b128 v[186:189], v168 offset:1024
	ds_read_b128 v[190:193], v168 offset:2048
	ds_read_b128 v[194:197], v168 offset:3072
	ds_read_b128 v[198:201], v168 offset:4096
	ds_read_b128 v[202:205], v168 offset:5120
	ds_read_b128 v[206:209], v168 offset:6144
	ds_read_b128 v[210:213], v168 offset:7168
	global_load_lds_dwordx4 v[214:215], off
	v_lshl_add_u64 v[214:215], s[36:37], 0, v[148:149]
	s_add_i32 m0, s19, 0xe000
	s_nop 0
	global_load_lds_dwordx4 v[214:215], off
	s_waitcnt vmcnt(8)
	s_waitcnt lgkmcnt(0)
	s_barrier
	s_setprio 1
	s_waitcnt lgkmcnt(0)
	v_mfma_f32_16x16x32_bf16 v[124:127], v[128:131], v[182:185], v[124:127]
	v_mfma_f32_16x16x32_bf16 v[124:127], v[132:135], v[186:189], v[124:127]
	v_mfma_f32_16x16x32_bf16 v[116:119], v[152:155], v[182:185], v[116:119]
	v_mfma_f32_16x16x32_bf16 v[116:119], v[156:159], v[186:189], v[116:119]
	v_mfma_f32_16x16x32_bf16 v[108:111], v[128:131], v[190:193], v[108:111]
	v_mfma_f32_16x16x32_bf16 v[108:111], v[132:135], v[194:197], v[108:111]
	v_mfma_f32_16x16x32_bf16 v[100:103], v[152:155], v[190:193], v[100:103]
	v_mfma_f32_16x16x32_bf16 v[100:103], v[156:159], v[194:197], v[100:103]
	v_mfma_f32_16x16x32_bf16 v[92:95], v[128:131], v[198:201], v[92:95]
	v_mfma_f32_16x16x32_bf16 v[92:95], v[132:135], v[202:205], v[92:95]
	v_mfma_f32_16x16x32_bf16 v[84:87], v[152:155], v[198:201], v[84:87]
	v_mfma_f32_16x16x32_bf16 v[84:87], v[156:159], v[202:205], v[84:87]
	v_mfma_f32_16x16x32_bf16 v[76:79], v[128:131], v[206:209], v[76:79]
	v_mfma_f32_16x16x32_bf16 v[76:79], v[132:135], v[210:213], v[76:79]
	v_mfma_f32_16x16x32_bf16 v[68:71], v[152:155], v[206:209], v[68:71]
	v_mfma_f32_16x16x32_bf16 v[68:71], v[156:159], v[210:213], v[68:71]
	s_setprio 0
	s_setprio 1
	v_mfma_f32_16x16x32_bf16 v[120:123], v[160:163], v[182:185], v[120:123]
	v_mfma_f32_16x16x32_bf16 v[120:123], v[170:173], v[186:189], v[120:123]
	v_mfma_f32_16x16x32_bf16 v[112:115], v[174:177], v[182:185], v[112:115]
	v_mfma_f32_16x16x32_bf16 v[112:115], v[178:181], v[186:189], v[112:115]
	v_mfma_f32_16x16x32_bf16 v[104:107], v[160:163], v[190:193], v[104:107]
	v_mfma_f32_16x16x32_bf16 v[104:107], v[170:173], v[194:197], v[104:107]
	v_mfma_f32_16x16x32_bf16 v[96:99], v[174:177], v[190:193], v[96:99]
	v_mfma_f32_16x16x32_bf16 v[96:99], v[178:181], v[194:197], v[96:99]
	v_mfma_f32_16x16x32_bf16 v[88:91], v[160:163], v[198:201], v[88:91]
	v_mfma_f32_16x16x32_bf16 v[88:91], v[170:173], v[202:205], v[88:91]
	v_mfma_f32_16x16x32_bf16 v[80:83], v[174:177], v[198:201], v[80:83]
	v_mfma_f32_16x16x32_bf16 v[80:83], v[178:181], v[202:205], v[80:83]
	v_mfma_f32_16x16x32_bf16 v[72:75], v[160:163], v[206:209], v[72:75]
	v_mfma_f32_16x16x32_bf16 v[72:75], v[170:173], v[210:213], v[72:75]
	v_mfma_f32_16x16x32_bf16 v[64:67], v[174:177], v[206:209], v[64:67]
	v_mfma_f32_16x16x32_bf16 v[64:67], v[178:181], v[210:213], v[64:67]
	s_setprio 0
	s_barrier
	s_add_i32 s63, s63, s16
	v_lshl_add_u64 v[214:215], s[40:41], 0, v[140:141]
	s_mov_b32 m0, s63
	ds_read_b128 v[182:185], v168 offset:16384
	ds_read_b128 v[186:189], v168 offset:17408
	ds_read_b128 v[190:193], v168 offset:18432
	ds_read_b128 v[194:197], v168 offset:19456
	ds_read_b128 v[198:201], v168 offset:20480
	ds_read_b128 v[202:205], v168 offset:21504
	ds_read_b128 v[206:209], v168 offset:22528
	ds_read_b128 v[210:213], v168 offset:23552
	global_load_lds_dwordx4 v[214:215], off
	s_add_i32 m0, s63, 0x2000
	s_add_u32 s66, s40, 0x4000
	v_lshl_add_u64 v[214:215], s[40:41], 0, v[136:137]
	s_addc_u32 s67, s41, 0
	s_add_i32 s63, s75, s16
	global_load_lds_dwordx4 v[214:215], off
	v_lshl_add_u64 v[214:215], s[66:67], 0, v[140:141]
	s_mov_b32 m0, s63
	s_nop 0
	global_load_lds_dwordx4 v[214:215], off
	v_lshl_add_u64 v[214:215], s[66:67], 0, v[136:137]
	s_add_i32 m0, s63, 0x2000
	s_nop 0
	global_load_lds_dwordx4 v[214:215], off
	v_lshl_add_u64 v[214:215], s[42:43], 0, v[142:143]
	s_mov_b32 m0, s19
	s_nop 0
	global_load_lds_dwordx4 v[214:215], off
	v_lshl_add_u64 v[214:215], s[42:43], 0, v[138:139]
	s_mov_b32 m0, s20
	s_nop 0
	global_load_lds_dwordx4 v[214:215], off
	s_waitcnt vmcnt(8)
	s_waitcnt lgkmcnt(0)
	s_barrier
; #define PG8_STAGE(bufoff, gbase, voff) do { _Pragma("unroll") for (int _i = 0; _i < 2; ++_i) \
;         __builtin_amdgcn_global_load_lds((const unsigned*)((const char*)(gbase) + (voff)[_i]), (PG8_LAS unsigned*)(lds + (bufoff) + ldsw + _i * 8192), 16, 0, 0); } while (0)
; #define PG8_LDA(dst, b, h) do { _Pragma("unroll") for (int m = 0; m < 4; ++m) _Pragma("unroll") for (int k = 0; k < 2; ++k) dst[m][k] = *(const PG8_LAS bf16x8*)(lds + PG8_SA(b, h) + aoff + m * 2048 + k * 1024); } while (0)
; #define PG8_LDB(dst, b, h) do { _Pragma("unroll") for (int n = 0; n < 2; ++n) _Pragma("unroll") for (int k = 0; k < 2; ++k) dst[n][k] = *(const PG8_LAS bf16x8*)(lds + PG8_SB(b, h) + boff + n * 2048 + k * 1024); } while (0)
; #define PG8_MMA(ai, bj, At, Bt) do { __builtin_amdgcn_s_setprio(1); _Pragma("unroll") for (int m = 0; m < 4; ++m) _Pragma("unroll") for (int n = 0; n < 2; ++n) _Pragma("unroll") for (int k = 0; k < 2; ++k) \
;         acc[ai][bj][m][n] = __builtin_amdgcn_mfma_f32_16x16x32_bf16(Bt[n][k], At[m][k], acc[ai][bj][m][n], 0, 0, 0); __builtin_amdgcn_s_setprio(0); } while (0)
; #define PG8_WAIT_V(n) asm volatile("s_waitcnt vmcnt(" #n ")" ::: "memory")
; #define PG8_WAIT_L(n) asm volatile("s_waitcnt lgkmcnt(" #n ")" ::: "memory")
; #define PG8_BAR __builtin_amdgcn_s_barrier()
; #define PG8_SCHED __builtin_amdgcn_sched_barrier(0)
; template <class Epi, class Sched, bool ALIGN_EPI = false, bool SP2 = false>
; __device__ __forceinline__ void gemm_phase(PG8_LAS unsigned char* lds, const Gemm g, const Sched& S, const Epi& E) {
;     ...
;             PG8_WAIT_V(8); PG8_WAIT_L(0); PG8_BAR; PG8_MMA(1, 0, At, B0); PG8_MMA(1, 1, At, B1); PG8_BAR; PG8_SCHED;
;             PG8_LDB(B0, 1, 0); PG8_LDB(B1, 1, 1); PG8_SCHED; PG8_LDA(At, 1, 0); PG8_STAGE(PG8_SA(0, 1), a2 + hstepB, voffA);
;             PG8_WAIT_V(8); PG8_WAIT_L(0); PG8_BAR; PG8_MMA(0, 0, At, B0); PG8_MMA(0, 1, At, B1); PG8_BAR; PG8_SCHED;
	s_setprio 1
	s_waitcnt lgkmcnt(0)
	v_mfma_f32_16x16x32_bf16 v[60:63], v[128:131], v[182:185], v[60:63]
	v_mfma_f32_16x16x32_bf16 v[60:63], v[132:135], v[186:189], v[60:63]
	v_mfma_f32_16x16x32_bf16 v[52:55], v[152:155], v[182:185], v[52:55]
	v_mfma_f32_16x16x32_bf16 v[52:55], v[156:159], v[186:189], v[52:55]
	v_mfma_f32_16x16x32_bf16 v[44:47], v[128:131], v[190:193], v[44:47]
	v_mfma_f32_16x16x32_bf16 v[44:47], v[132:135], v[194:197], v[44:47]
	v_mfma_f32_16x16x32_bf16 v[36:39], v[152:155], v[190:193], v[36:39]
	v_mfma_f32_16x16x32_bf16 v[36:39], v[156:159], v[194:197], v[36:39]
	v_mfma_f32_16x16x32_bf16 v[28:31], v[128:131], v[198:201], v[28:31]
	v_mfma_f32_16x16x32_bf16 v[28:31], v[132:135], v[202:205], v[28:31]
	v_mfma_f32_16x16x32_bf16 v[20:23], v[152:155], v[198:201], v[20:23]
	v_mfma_f32_16x16x32_bf16 v[20:23], v[156:159], v[202:205], v[20:23]
	v_mfma_f32_16x16x32_bf16 v[12:15], v[128:131], v[206:209], v[12:15]
	v_mfma_f32_16x16x32_bf16 v[12:15], v[132:135], v[210:213], v[12:15]
	v_mfma_f32_16x16x32_bf16 v[4:7], v[152:155], v[206:209], v[4:7]
	v_mfma_f32_16x16x32_bf16 v[4:7], v[156:159], v[210:213], v[4:7]
	s_setprio 0
	s_setprio 1
	v_mfma_f32_16x16x32_bf16 v[56:59], v[160:163], v[182:185], v[56:59]
	v_mfma_f32_16x16x32_bf16 v[56:59], v[170:173], v[186:189], v[56:59]
	v_mfma_f32_16x16x32_bf16 v[48:51], v[174:177], v[182:185], v[48:51]
	v_mfma_f32_16x16x32_bf16 v[48:51], v[178:181], v[186:189], v[48:51]
	v_mfma_f32_16x16x32_bf16 v[40:43], v[160:163], v[190:193], v[40:43]
	v_mfma_f32_16x16x32_bf16 v[40:43], v[170:173], v[194:197], v[40:43]
	v_mfma_f32_16x16x32_bf16 v[32:35], v[174:177], v[190:193], v[32:35]
	v_mfma_f32_16x16x32_bf16 v[32:35], v[178:181], v[194:197], v[32:35]
	v_mfma_f32_16x16x32_bf16 v[24:27], v[160:163], v[198:201], v[24:27]
	v_mfma_f32_16x16x32_bf16 v[24:27], v[170:173], v[202:205], v[24:27]
	v_mfma_f32_16x16x32_bf16 v[16:19], v[174:177], v[198:201], v[16:19]
	v_mfma_f32_16x16x32_bf16 v[16:19], v[178:181], v[202:205], v[16:19]
	v_mfma_f32_16x16x32_bf16 v[8:11], v[160:163], v[206:209], v[8:11]
	v_mfma_f32_16x16x32_bf16 v[8:11], v[170:173], v[210:213], v[8:11]
	v_mfma_f32_16x16x32_bf16 v[0:3], v[174:177], v[206:209], v[0:3]
	v_mfma_f32_16x16x32_bf16 v[0:3], v[178:181], v[210:213], v[0:3]
	s_setprio 0
	s_barrier
	s_add_i32 s63, 0, 0x18000
	v_add_u32_e32 v151, s63, v165
	s_add_i32 s66, 0, 0x1c000
	ds_read_b128 v[128:131], v151
	ds_read_b128 v[132:135], v151 offset:1024
	ds_read_b128 v[152:155], v151 offset:2048
	ds_read_b128 v[156:159], v151 offset:3072
	v_add_u32_e32 v151, s66, v165
	ds_read_b128 v[160:163], v151
	ds_read_b128 v[170:173], v151 offset:1024
	ds_read_b128 v[174:177], v151 offset:2048
	ds_read_b128 v[178:181], v151 offset:3072
	s_add_u32 s42, s42, 0x4000
	s_addc_u32 s43, s43, 0
	s_mov_b32 m0, s21
	v_lshl_add_u64 v[214:215], s[42:43], 0, v[142:143]
	ds_read_b128 v[182:185], v168 offset:32768
	ds_read_b128 v[186:189], v168 offset:33792
	ds_read_b128 v[190:193], v168 offset:34816
	ds_read_b128 v[194:197], v168 offset:35840
	ds_read_b128 v[198:201], v168 offset:36864
	ds_read_b128 v[202:205], v168 offset:37888
	ds_read_b128 v[206:209], v168 offset:38912
	ds_read_b128 v[210:213], v168 offset:39936
	global_load_lds_dwordx4 v[214:215], off
	v_lshl_add_u64 v[214:215], s[42:43], 0, v[138:139]
	s_mov_b32 m0, s22
	s_nop 0
	global_load_lds_dwordx4 v[214:215], off
	s_nop 0
	s_waitcnt vmcnt(8)
	s_waitcnt lgkmcnt(0)
	s_barrier
	s_setprio 1
	s_waitcnt lgkmcnt(0)
	v_mfma_f32_16x16x32_bf16 v[124:127], v[128:131], v[182:185], v[124:127]
	v_mfma_f32_16x16x32_bf16 v[124:127], v[132:135], v[186:189], v[124:127]
	v_mfma_f32_16x16x32_bf16 v[116:119], v[152:155], v[182:185], v[116:119]
	v_mfma_f32_16x16x32_bf16 v[116:119], v[156:159], v[186:189], v[116:119]
	v_mfma_f32_16x16x32_bf16 v[108:111], v[128:131], v[190:193], v[108:111]
	v_mfma_f32_16x16x32_bf16 v[108:111], v[132:135], v[194:197], v[108:111]
	v_mfma_f32_16x16x32_bf16 v[100:103], v[152:155], v[190:193], v[100:103]
	v_mfma_f32_16x16x32_bf16 v[100:103], v[156:159], v[194:197], v[100:103]
	v_mfma_f32_16x16x32_bf16 v[92:95], v[128:131], v[198:201], v[92:95]
	v_mfma_f32_16x16x32_bf16 v[92:95], v[132:135], v[202:205], v[92:95]
	v_mfma_f32_16x16x32_bf16 v[84:87], v[152:155], v[198:201], v[84:87]
	v_mfma_f32_16x16x32_bf16 v[84:87], v[156:159], v[202:205], v[84:87]
	v_mfma_f32_16x16x32_bf16 v[76:79], v[128:131], v[206:209], v[76:79]
	v_mfma_f32_16x16x32_bf16 v[76:79], v[132:135], v[210:213], v[76:79]
	v_mfma_f32_16x16x32_bf16 v[68:71], v[152:155], v[206:209], v[68:71]
	v_mfma_f32_16x16x32_bf16 v[68:71], v[156:159], v[210:213], v[68:71]
	s_setprio 0
	s_setprio 1
	v_mfma_f32_16x16x32_bf16 v[120:123], v[160:163], v[182:185], v[120:123]
	v_mfma_f32_16x16x32_bf16 v[120:123], v[170:173], v[186:189], v[120:123]
	v_mfma_f32_16x16x32_bf16 v[112:115], v[174:177], v[182:185], v[112:115]
	v_mfma_f32_16x16x32_bf16 v[112:115], v[178:181], v[186:189], v[112:115]
	v_mfma_f32_16x16x32_bf16 v[104:107], v[160:163], v[190:193], v[104:107]
	v_mfma_f32_16x16x32_bf16 v[104:107], v[170:173], v[194:197], v[104:107]
	v_mfma_f32_16x16x32_bf16 v[96:99], v[174:177], v[190:193], v[96:99]
	v_mfma_f32_16x16x32_bf16 v[96:99], v[178:181], v[194:197], v[96:99]
	v_mfma_f32_16x16x32_bf16 v[88:91], v[160:163], v[198:201], v[88:91]
	v_mfma_f32_16x16x32_bf16 v[88:91], v[170:173], v[202:205], v[88:91]
	v_mfma_f32_16x16x32_bf16 v[80:83], v[174:177], v[198:201], v[80:83]
	v_mfma_f32_16x16x32_bf16 v[80:83], v[178:181], v[202:205], v[80:83]
	v_mfma_f32_16x16x32_bf16 v[72:75], v[160:163], v[206:209], v[72:75]
	v_mfma_f32_16x16x32_bf16 v[72:75], v[170:173], v[210:213], v[72:75]
	v_mfma_f32_16x16x32_bf16 v[64:67], v[174:177], v[206:209], v[64:67]
	v_mfma_f32_16x16x32_bf16 v[64:67], v[178:181], v[210:213], v[64:67]
	s_setprio 0
	s_barrier
; #define PG8_STAGE(bufoff, gbase, voff) do { _Pragma("unroll") for (int _i = 0; _i < 2; ++_i) \
;         __builtin_amdgcn_global_load_lds((const unsigned*)((const char*)(gbase) + (voff)[_i]), (PG8_LAS unsigned*)(lds + (bufoff) + ldsw + _i * 8192), 16, 0, 0); } while (0)
; #define PG8_LDA(dst, b, h) do { _Pragma("unroll") for (int m = 0; m < 4; ++m) _Pragma("unroll") for (int k = 0; k < 2; ++k) dst[m][k] = *(const PG8_LAS bf16x8*)(lds + PG8_SA(b, h) + aoff + m * 2048 + k * 1024); } while (0)
; #define PG8_MMA(ai, bj, At, Bt) do { __builtin_amdgcn_s_setprio(1); _Pragma("unroll") for (int m = 0; m < 4; ++m) _Pragma("unroll") for (int n = 0; n < 2; ++n) _Pragma("unroll") for (int k = 0; k < 2; ++k) \
;         acc[ai][bj][m][n] = __builtin_amdgcn_mfma_f32_16x16x32_bf16(Bt[n][k], At[m][k], acc[ai][bj][m][n], 0, 0, 0); __builtin_amdgcn_s_setprio(0); } while (0)
; #define PG8_WAIT_V(n) asm volatile("s_waitcnt vmcnt(" #n ")" ::: "memory")
; #define PG8_WAIT_L(n) asm volatile("s_waitcnt lgkmcnt(" #n ")" ::: "memory")
; #define PG8_BAR __builtin_amdgcn_s_barrier()
; #define PG8_SCHED __builtin_amdgcn_sched_barrier(0)
; template <class Epi, class Sched, bool ALIGN_EPI = false, bool SP2 = false>
; __device__ __forceinline__ void gemm_phase(PG8_LAS unsigned char* lds, const Gemm g, const Sched& S, const Epi& E) {
;     ...
;             PG8_LDA(At, 1, 1); PG8_STAGE(PG8_SB(1, 0), b3, voffB); PG8_STAGE(PG8_SB(1, 1), b3 + hstepB, voffB); PG8_STAGE(PG8_SA(1, 0), a3, voffA);
;             PG8_WAIT_V(8); PG8_WAIT_L(0); PG8_BAR; PG8_MMA(1, 0, At, B0); PG8_MMA(1, 1, At, B1); PG8_BAR; PG8_SCHED;
;     ...
;         if constexpr (ALIGN_EPI) { if (wr == 0) PG8_BAR; }
	s_nop 0
	s_add_u32 s42, s40, 0x8000
	s_addc_u32 s43, s41, 0
	s_add_i32 s63, s63, s16
	v_lshl_add_u64 v[214:215], s[42:43], 0, v[140:141]
	s_mov_b32 m0, s63
	ds_read_b128 v[182:185], v168 offset:49152
	ds_read_b128 v[186:189], v168 offset:50176
	ds_read_b128 v[190:193], v168 offset:51200
	ds_read_b128 v[194:197], v168 offset:52224
	ds_read_b128 v[198:201], v168 offset:53248
	ds_read_b128 v[202:205], v168 offset:54272
	ds_read_b128 v[206:209], v168 offset:55296
	ds_read_b128 v[210:213], v168 offset:56320
	global_load_lds_dwordx4 v[214:215], off
	s_add_i32 m0, s63, 0x2000
	s_add_u32 s40, s40, 0xc000
	v_lshl_add_u64 v[214:215], s[42:43], 0, v[136:137]
	s_addc_u32 s41, s41, 0
	s_add_i32 s42, s66, s16
	global_load_lds_dwordx4 v[214:215], off
	v_lshl_add_u64 v[214:215], s[40:41], 0, v[140:141]
	s_mov_b32 m0, s42
	s_nop 0
	global_load_lds_dwordx4 v[214:215], off
	v_lshl_add_u64 v[214:215], s[40:41], 0, v[136:137]
	s_add_i32 m0, s42, 0x2000
	s_nop 0
	global_load_lds_dwordx4 v[214:215], off
	v_lshl_add_u64 v[214:215], s[38:39], 0, v[142:143]
	s_mov_b32 m0, s25
	s_nop 0
	global_load_lds_dwordx4 v[214:215], off
	v_lshl_add_u64 v[214:215], s[38:39], 0, v[138:139]
	s_mov_b32 m0, s26
	s_nop 0
	global_load_lds_dwordx4 v[214:215], off
	s_waitcnt vmcnt(8)
	s_waitcnt lgkmcnt(0)
	s_barrier
	s_setprio 1
	s_waitcnt lgkmcnt(0)
	v_mfma_f32_16x16x32_bf16 v[60:63], v[128:131], v[182:185], v[60:63]
	v_mfma_f32_16x16x32_bf16 v[60:63], v[132:135], v[186:189], v[60:63]
	v_mfma_f32_16x16x32_bf16 v[52:55], v[152:155], v[182:185], v[52:55]
	v_mfma_f32_16x16x32_bf16 v[52:55], v[156:159], v[186:189], v[52:55]
	v_mfma_f32_16x16x32_bf16 v[44:47], v[128:131], v[190:193], v[44:47]
	v_mfma_f32_16x16x32_bf16 v[44:47], v[132:135], v[194:197], v[44:47]
	v_mfma_f32_16x16x32_bf16 v[36:39], v[152:155], v[190:193], v[36:39]
	v_mfma_f32_16x16x32_bf16 v[36:39], v[156:159], v[194:197], v[36:39]
	v_mfma_f32_16x16x32_bf16 v[28:31], v[128:131], v[198:201], v[28:31]
	v_mfma_f32_16x16x32_bf16 v[28:31], v[132:135], v[202:205], v[28:31]
	v_mfma_f32_16x16x32_bf16 v[20:23], v[152:155], v[198:201], v[20:23]
	v_mfma_f32_16x16x32_bf16 v[20:23], v[156:159], v[202:205], v[20:23]
	v_mfma_f32_16x16x32_bf16 v[12:15], v[128:131], v[206:209], v[12:15]
	v_mfma_f32_16x16x32_bf16 v[12:15], v[132:135], v[210:213], v[12:15]
	v_mfma_f32_16x16x32_bf16 v[4:7], v[152:155], v[206:209], v[4:7]
	v_mfma_f32_16x16x32_bf16 v[4:7], v[156:159], v[210:213], v[4:7]
	s_setprio 0
	s_setprio 1
	v_mfma_f32_16x16x32_bf16 v[56:59], v[160:163], v[182:185], v[56:59]
	v_mfma_f32_16x16x32_bf16 v[56:59], v[170:173], v[186:189], v[56:59]
	v_mfma_f32_16x16x32_bf16 v[48:51], v[174:177], v[182:185], v[48:51]
	v_mfma_f32_16x16x32_bf16 v[48:51], v[178:181], v[186:189], v[48:51]
	v_mfma_f32_16x16x32_bf16 v[40:43], v[160:163], v[190:193], v[40:43]
	v_mfma_f32_16x16x32_bf16 v[40:43], v[170:173], v[194:197], v[40:43]
	v_mfma_f32_16x16x32_bf16 v[32:35], v[174:177], v[190:193], v[32:35]
	v_mfma_f32_16x16x32_bf16 v[32:35], v[178:181], v[194:197], v[32:35]
	v_mfma_f32_16x16x32_bf16 v[24:27], v[160:163], v[198:201], v[24:27]
	v_mfma_f32_16x16x32_bf16 v[24:27], v[170:173], v[202:205], v[24:27]
	v_mfma_f32_16x16x32_bf16 v[16:19], v[174:177], v[198:201], v[16:19]
	v_mfma_f32_16x16x32_bf16 v[16:19], v[178:181], v[202:205], v[16:19]
	v_mfma_f32_16x16x32_bf16 v[8:11], v[160:163], v[206:209], v[8:11]
	v_mfma_f32_16x16x32_bf16 v[8:11], v[170:173], v[210:213], v[8:11]
	v_mfma_f32_16x16x32_bf16 v[0:3], v[174:177], v[206:209], v[0:3]
	v_mfma_f32_16x16x32_bf16 v[0:3], v[178:181], v[210:213], v[0:3]
	s_setprio 0
	s_barrier
	s_add_i32 s62, s62, 2
	s_add_u32 s36, s36, 0x10000
	s_addc_u32 s37, s37, 0
	s_add_u32 s44, s44, 0x10000
	s_addc_u32 s45, s45, 0
	s_cmp_gt_u32 s62, 29
	s_cbranch_scc0 .LBB0_263
	s_and_b64 vcc, exec, s[8:9]
	s_cbranch_vccz .LBB0_266
	s_barrier
